# MLA loop: all waves retire their in-flight LDS-DMA pieces before the softmax-block barrier (extra vmcnt wait; group 1 no longer drains inside the MFMA block)
# speedup vs baseline: 1.0561x; 1.0027x over previous
; #define ATT_BAR() do { asm volatile("s_waitcnt lgkmcnt(0)" ::: "memory"); __builtin_amdgcn_s_barrier(); asm volatile("" ::: "memory"); } while (0)
; #define ATT_WAITV() asm volatile("s_waitcnt vmcnt(0)" ::: "memory")
; #define ATT_ISSUEK(t_, buf_) do { _Pragma("unroll") for (int j_ = 0; j_ < (NIK + 7) / 8; ++j_) { const int id_ = w + 8 * j_; if (id_ < NIK) \
;         glds16(src.k_ptr((t_), koff[j_]), __builtin_amdgcn_readfirstlane(lkA + (buf_) * KBUF + id_ * 1024)); } } while (0)
; #define ATT_ISSUEV(t_, buf_) do { _Pragma("unroll") for (int j_ = 0; j_ < (NIV + 7) / 8; ++j_) { const int id_ = w + 8 * j_; if (id_ < NIV) \
;         glds16(src.v_ptr((t_), voff[j_]), __builtin_amdgcn_readfirstlane(lvA + (buf_) * VBUF + id_ * 1024)); } } while (0)
; template <int DQK, bool STATS, bool PRE, class Src, class Mask, class Post> ...
;     ...
;         if (grp == 0) ATT_WAITV();
;         ATT_BAR();
;         __builtin_amdgcn_s_setprio(1);
;         if (grp == 0) { if (t + 2 < te) ATT_ISSUEK(t + 2, i & 1); if (!STATS && t + 1 < te) ATT_ISSUEV(t + 1, (i + 1) & 1); }
.LBB0_2861:
	s_or_b64 exec, exec, s[64:65]
	s_waitcnt vmcnt(0)
	s_waitcnt lgkmcnt(0)
	s_barrier
	s_setprio 1
	s_and_saveexec_b64 s[64:65], s[10:11]
	s_cbranch_execz .LBB0_2876
	s_add_i32 s66, s89, 2
	s_cmp_ge_u32 s66, s50
	s_cbranch_scc1 .LBB0_2871
	s_and_b32 s66, 1, s89
	s_add_i32 s67, 0, 0x6400
	s_cmp_eq_u32 s66, 1
	s_cselect_b32 s66, s67, 0
	s_andn2_b64 vcc, exec, s[38:39]
	s_cbranch_vccnz .LBB0_2868
	v_mov_b32_e32 v207, s84
	v_mov_b32_e32 v208, s86
	v_cndmask_b32_e64 v209, v207, v208, s[12:13]
	v_mov_b32_e32 v207, s83
	v_mov_b32_e32 v208, s85
	v_cndmask_b32_e64 v208, v207, v208, s[12:13]
	s_add_i32 s67, s66, s51
	v_lshl_add_u64 v[208:209], v[208:209], 0, v[0:1]
	s_mov_b32 s90, m0
	s_mov_b32 m0, s67
	s_nop 0
	global_load_lds_dwordx4 v[208:209], off
	s_mov_b32 m0, s90
	s_andn2_b64 vcc, exec, s[46:47]
	s_cbranch_vccz .LBB0_2869
